# grid barrier: non-leader workgroups poll the top release word directly
# speedup vs baseline: 1.0083x; 1.0002x over previous
.LBB0_459:
	s_or_b64 exec, exec, s[18:19]
	v_cvt_f32_u32_e32 v4, v2
	s_waitcnt vmcnt(0)
	v_readfirstlane_b32 s0, v3
	s_add_u32 s14, s14, 0x2400
	s_addc_u32 s15, s15, 0
	v_rcp_iflag_f32_e32 v4, v4
	v_add_u32_e32 v5, s0, v1
	v_mul_f32_e32 v3, 0x4f7ffffe, v4
	v_cvt_u32_f32_e32 v3, v3
	v_sub_u32_e32 v4, 0, v2
	v_mul_lo_u32 v1, v4, v3
	v_mul_hi_u32 v1, v3, v1
	v_add_u32_e32 v1, v3, v1
	v_mul_hi_u32 v1, v5, v1
	v_mul_lo_u32 v3, v1, v2
	v_sub_u32_e32 v3, v5, v3
	v_add_u32_e32 v4, 1, v1
	v_cmp_ge_u32_e32 vcc, v3, v2
	s_nop 1
	v_cndmask_b32_e32 v1, v1, v4, vcc
	v_sub_u32_e32 v4, v3, v2
	v_cndmask_b32_e32 v3, v3, v4, vcc
	v_add_u32_e32 v4, 1, v1
	v_cmp_ge_u32_e32 vcc, v3, v2
	v_add_u32_e32 v3, 1, v5
	s_nop 0
	v_cndmask_b32_e32 v1, v1, v4, vcc
	v_mul_lo_u32 v4, v2, v1
	v_add_u32_e32 v2, v4, v2
	v_cmp_ne_u32_e32 vcc, v3, v2
	s_and_saveexec_b64 s[0:1], vcc
	s_xor_b64 s[16:17], exec, s[0:1]
	s_cbranch_execz .LBB0_473
	s_waitcnt lgkmcnt(0)
	s_add_u32 s98, s10, 0x303500
	s_addc_u32 s99, s11, 0
	global_load_dword v0, v193, s[98:99] sc1
	s_waitcnt vmcnt(0)
	v_cmp_eq_u32_e32 vcc, v0, v1
	s_and_saveexec_b64 s[18:19], vcc
	s_cbranch_execz .LBB0_472
	s_mov_b32 s0, 1
	s_mov_b64 s[20:21], 0
	s_branch .LBB0_463

.LBB0_465:
	global_load_dword v0, v193, s[98:99] sc1
	s_add_i32 s0, s0, 1
	s_mov_b64 s[30:31], -1
	s_waitcnt vmcnt(0)
	v_cmp_ne_u32_e32 vcc, v0, v1
	s_orn2_b64 s[26:27], vcc, exec
	s_branch .LBB0_462

	.amdhsa_kernel _Z14fwd_megakernel6Params
		.amdhsa_group_segment_fixed_size 0
		.amdhsa_private_segment_fixed_size 0
		.amdhsa_kernarg_size 488
		.amdhsa_user_sgpr_count 2
		.amdhsa_user_sgpr_dispatch_ptr 0
		.amdhsa_user_sgpr_queue_ptr 0
		.amdhsa_user_sgpr_kernarg_segment_ptr 1
		.amdhsa_user_sgpr_dispatch_id 0
		.amdhsa_user_sgpr_kernarg_preload_length 0
		.amdhsa_user_sgpr_kernarg_preload_offset 0
		.amdhsa_user_sgpr_private_segment_size 0
		.amdhsa_uses_dynamic_stack 0
		.amdhsa_enable_private_segment 0
		.amdhsa_system_sgpr_workgroup_id_x 1
		.amdhsa_system_sgpr_workgroup_id_y 0
		.amdhsa_system_sgpr_workgroup_id_z 0
		.amdhsa_system_sgpr_workgroup_info 0
		.amdhsa_system_vgpr_workitem_id 2
		.amdhsa_next_free_vgpr 255
		.amdhsa_next_free_sgpr 102
		.amdhsa_accum_offset 256
		.amdhsa_reserve_vcc 1
		.amdhsa_float_round_mode_32 0
		.amdhsa_float_round_mode_16_64 0
		.amdhsa_float_denorm_mode_32 3
		.amdhsa_float_denorm_mode_16_64 3
		.amdhsa_dx10_clamp 1
		.amdhsa_ieee_mode 1
		.amdhsa_fp16_overflow 0
		.amdhsa_tg_split 0
		.amdhsa_exception_fp_ieee_invalid_op 0
		.amdhsa_exception_fp_denorm_src 0
		.amdhsa_exception_fp_ieee_div_zero 0
		.amdhsa_exception_fp_ieee_overflow 0
		.amdhsa_exception_fp_ieee_underflow 0
		.amdhsa_exception_fp_ieee_inexact 0
		.amdhsa_exception_int_div_zero 0
	.end_amdhsa_kernel

amdhsa.kernels:
  - .agpr_count:     0
    .args:
      - .offset:         0
        .size:           232
        .value_kind:     by_value
      - .offset:         232
        .size:           4
        .value_kind:     hidden_block_count_x
      - .offset:         236
        .size:           4
        .value_kind:     hidden_block_count_y
      - .offset:         240
        .size:           4
        .value_kind:     hidden_block_count_z
      - .offset:         244
        .size:           2
        .value_kind:     hidden_group_size_x
      - .offset:         246
        .size:           2
        .value_kind:     hidden_group_size_y
      - .offset:         248
        .size:           2
        .value_kind:     hidden_group_size_z
      - .offset:         250
        .size:           2
        .value_kind:     hidden_remainder_x
      - .offset:         252
        .size:           2
        .value_kind:     hidden_remainder_y
      - .offset:         254
        .size:           2
        .value_kind:     hidden_remainder_z
      - .offset:         272
        .size:           8
        .value_kind:     hidden_global_offset_x
      - .offset:         280
        .size:           8
        .value_kind:     hidden_global_offset_y
      - .offset:         288
        .size:           8
        .value_kind:     hidden_global_offset_z
      - .offset:         296
        .size:           2
        .value_kind:     hidden_grid_dims
      - .offset:         320
        .size:           8
        .value_kind:     hidden_multigrid_sync_arg
      - .offset:         352
        .size:           4
        .value_kind:     hidden_dynamic_lds_size
    .group_segment_fixed_size: 0
    .kernarg_segment_align: 8
    .kernarg_segment_size: 488
    .language:       OpenCL C
    .language_version:
      - 2
      - 0
    .max_flat_workgroup_size: 512
    .name:           _Z14fwd_megakernel6Params
    .private_segment_fixed_size: 0
    .sgpr_count:     108
    .sgpr_spill_count: 18
    .symbol:         _Z14fwd_megakernel6Params.kd
    .uniform_work_group_size: 1
    .uses_dynamic_stack: false
    .vgpr_count:     255
    .vgpr_spill_count: 0
    .wavefront_size: 64
